# v38 + MLA loop v4: no per-tile row-max tree; lanes check their tile exp-sum against 2^16 (or inf) and only then redo the tile with a real maximum; ~30 fewer VALU per wave-iteration
# speedup vs baseline: 1.0032x; 1.0014x over previous
.Lm_noload:
	s_cmp_gt_i32 s20, s35
	s_cbranch_scc1 .LBB0_379
	s_bitcmp1_b32 s20, 0
	s_cselect_b32 s38, 0xb400, 0
	v_add_u32_e32 v8, s38, v191
	ds_read_b128 v[10:13], v8
	ds_read_b128 v[14:17], v8 offset:32
	ds_read_b128 v[202:205], v8 offset:64
	ds_read_b128 v[206:209], v8 offset:96
	v_add_u32_e32 v197, s38, v196
	s_setprio 3
	s_waitcnt lgkmcnt(3)
	v_mfma_f32_32x32x16_bf16 v[100:115], v[10:13], v[116:119], v[210:225]
	ds_read_b128 v[10:13], v8 offset:128
	s_waitcnt lgkmcnt(3)
	v_mfma_f32_32x32x16_bf16 v[100:115], v[14:17], v[120:123], v[100:115]
	ds_read_b128 v[14:17], v8 offset:160
	s_waitcnt lgkmcnt(3)
	v_mfma_f32_32x32x16_bf16 v[100:115], v[202:205], v[124:127], v[100:115]
	ds_read_b128 v[202:205], v8 offset:192
	s_waitcnt lgkmcnt(3)
	v_mfma_f32_32x32x16_bf16 v[100:115], v[206:209], v[132:135], v[100:115]
	ds_read_b128 v[206:209], v8 offset:224
	s_waitcnt lgkmcnt(3)
	v_mfma_f32_32x32x16_bf16 v[100:115], v[10:13], v[136:139], v[100:115]
	ds_read_b128 v[10:13], v8 offset:256
	s_waitcnt lgkmcnt(3)
	v_mfma_f32_32x32x16_bf16 v[100:115], v[14:17], v[140:143], v[100:115]
	ds_read_b128 v[14:17], v8 offset:288
	s_waitcnt lgkmcnt(3)
	v_mfma_f32_32x32x16_bf16 v[100:115], v[202:205], v[144:147], v[100:115]
	ds_read_b128 v[202:205], v8 offset:320
	s_waitcnt lgkmcnt(3)
	v_mfma_f32_32x32x16_bf16 v[100:115], v[206:209], v[148:151], v[100:115]
	ds_read_b128 v[206:209], v8 offset:352
	s_waitcnt lgkmcnt(3)
	v_mfma_f32_32x32x16_bf16 v[100:115], v[10:13], v[152:155], v[100:115]
	ds_read_b128 v[10:13], v8 offset:12800
	s_waitcnt lgkmcnt(3)
	v_mfma_f32_32x32x16_bf16 v[100:115], v[14:17], v[156:159], v[100:115]
	ds_read_b128 v[14:17], v8 offset:12832
	s_waitcnt lgkmcnt(3)
	v_mfma_f32_32x32x16_bf16 v[100:115], v[202:205], v[160:163], v[100:115]
	ds_read_b128 v[202:205], v8 offset:12864
	s_waitcnt lgkmcnt(3)
	v_mfma_f32_32x32x16_bf16 v[100:115], v[206:209], v[164:167], v[100:115]
	ds_read_b128 v[206:209], v8 offset:12896
	s_waitcnt lgkmcnt(3)
	v_mfma_f32_32x32x16_bf16 v[84:99], v[10:13], v[116:119], v[210:225]
	ds_read_b128 v[10:13], v8 offset:12928
	s_waitcnt lgkmcnt(3)
	v_mfma_f32_32x32x16_bf16 v[84:99], v[14:17], v[120:123], v[84:99]
	ds_read_b128 v[14:17], v8 offset:12960
	s_waitcnt lgkmcnt(3)
	v_mfma_f32_32x32x16_bf16 v[84:99], v[202:205], v[124:127], v[84:99]
	ds_read_b128 v[202:205], v8 offset:12992
	s_waitcnt lgkmcnt(3)
	v_mfma_f32_32x32x16_bf16 v[84:99], v[206:209], v[132:135], v[84:99]
	ds_read_b128 v[206:209], v8 offset:13024
	s_waitcnt lgkmcnt(3)
	v_mfma_f32_32x32x16_bf16 v[84:99], v[10:13], v[136:139], v[84:99]
	ds_read_b128 v[10:13], v8 offset:13056
	s_waitcnt lgkmcnt(3)
	v_mfma_f32_32x32x16_bf16 v[84:99], v[14:17], v[140:143], v[84:99]
	ds_read_b128 v[14:17], v8 offset:13088
	s_waitcnt lgkmcnt(3)
	v_mfma_f32_32x32x16_bf16 v[84:99], v[202:205], v[144:147], v[84:99]
	ds_read_b128 v[202:205], v8 offset:13120
	s_waitcnt lgkmcnt(3)
	v_mfma_f32_32x32x16_bf16 v[84:99], v[206:209], v[148:151], v[84:99]
	ds_read_b128 v[206:209], v8 offset:13152
	s_waitcnt lgkmcnt(3)
	v_mfma_f32_32x32x16_bf16 v[84:99], v[10:13], v[152:155], v[84:99]
	ds_read_b64_tr_b16 v[10:11], v197 offset:25600
	ds_read_b64_tr_b16 v[12:13], v197 offset:28160
	s_waitcnt lgkmcnt(4)
	v_mfma_f32_32x32x16_bf16 v[84:99], v[14:17], v[156:159], v[84:99]
	ds_read_b64_tr_b16 v[14:15], v197 offset:25664
	ds_read_b64_tr_b16 v[16:17], v197 offset:28224
	s_waitcnt lgkmcnt(5)
	v_mfma_f32_32x32x16_bf16 v[84:99], v[202:205], v[160:163], v[84:99]
	ds_read_b64_tr_b16 v[202:203], v197 offset:25728
	ds_read_b64_tr_b16 v[204:205], v197 offset:28288
	s_waitcnt lgkmcnt(6)
	v_mfma_f32_32x32x16_bf16 v[84:99], v[206:209], v[164:167], v[84:99]
	ds_read_b64_tr_b16 v[206:207], v197 offset:25792
	ds_read_b64_tr_b16 v[208:209], v197 offset:28352
	s_and_b64 vcc, exec, s[18:19]
	s_cbranch_vccz .Lm_p1
	s_setprio 0
	s_branch .Lm_pd

.Lm_pd:
.Lm_exp:
	v_exp_f32_e32 v100, v100
	v_exp_f32_e32 v101, v101
	v_exp_f32_e32 v102, v102
	v_exp_f32_e32 v103, v103
	v_exp_f32_e32 v104, v104
	v_exp_f32_e32 v105, v105
	v_exp_f32_e32 v106, v106
	v_exp_f32_e32 v107, v107
	v_exp_f32_e32 v108, v108
	v_exp_f32_e32 v109, v109
	v_exp_f32_e32 v110, v110
	v_exp_f32_e32 v111, v111
	v_exp_f32_e32 v112, v112
	v_exp_f32_e32 v113, v113
	v_exp_f32_e32 v114, v114
	v_exp_f32_e32 v115, v115
	v_exp_f32_e32 v84, v84
	v_exp_f32_e32 v85, v85
	v_exp_f32_e32 v86, v86
	v_exp_f32_e32 v87, v87
	v_exp_f32_e32 v88, v88
	v_exp_f32_e32 v89, v89
	v_exp_f32_e32 v90, v90
	v_exp_f32_e32 v91, v91
	v_exp_f32_e32 v92, v92
	v_exp_f32_e32 v93, v93
	v_exp_f32_e32 v94, v94
	v_exp_f32_e32 v95, v95
	v_exp_f32_e32 v96, v96
	v_exp_f32_e32 v97, v97
	v_exp_f32_e32 v98, v98
	v_exp_f32_e32 v99, v99
	v_add_f32_e32 v234, 0, v100
	v_add_f32_e32 v234, v101, v234
	v_add_f32_e32 v234, v102, v234
	v_add_f32_e32 v234, v103, v234
	v_add_f32_e32 v234, v104, v234
	v_add_f32_e32 v234, v105, v234
	v_add_f32_e32 v234, v106, v234
	v_add_f32_e32 v234, v107, v234
	v_add_f32_e32 v234, v108, v234
	v_add_f32_e32 v234, v109, v234
	v_add_f32_e32 v234, v110, v234
	v_add_f32_e32 v234, v111, v234
	v_add_f32_e32 v234, v112, v234
	v_add_f32_e32 v234, v113, v234
	v_add_f32_e32 v234, v114, v234
	v_add_f32_e32 v234, v115, v234
	v_add_f32_e32 v234, v84, v234
	v_add_f32_e32 v234, v85, v234
	v_add_f32_e32 v234, v86, v234
	v_add_f32_e32 v234, v87, v234
	v_add_f32_e32 v234, v88, v234
	v_add_f32_e32 v234, v89, v234
	v_add_f32_e32 v234, v90, v234
	v_add_f32_e32 v234, v91, v234
	v_add_f32_e32 v234, v92, v234
	v_add_f32_e32 v234, v93, v234
	v_add_f32_e32 v234, v94, v234
	v_add_f32_e32 v234, v95, v234
	v_add_f32_e32 v234, v96, v234
	v_add_f32_e32 v234, v97, v234
	v_add_f32_e32 v234, v98, v234
	v_add_f32_e32 v234, v99, v234
	v_cmp_lt_f32_e32 vcc, 0x47800000, v234
	s_cbranch_vccnz .Lm_R
	v_add_f32_e32 v193, v193, v234
	v_cvt_pk_bf16_f32 v226, v100, v101
	v_cvt_pk_bf16_f32 v227, v102, v103
	v_cvt_pk_bf16_f32 v228, v104, v105
	v_cvt_pk_bf16_f32 v229, v106, v107
	v_cvt_pk_bf16_f32 v230, v108, v109
	v_cvt_pk_bf16_f32 v231, v110, v111
	v_cvt_pk_bf16_f32 v232, v112, v113
	v_cvt_pk_bf16_f32 v233, v114, v115
	ds_read_b64_tr_b16 v[100:101], v197 offset:30720
	ds_read_b64_tr_b16 v[102:103], v197 offset:33280
	ds_read_b64_tr_b16 v[104:105], v197 offset:30784
	ds_read_b64_tr_b16 v[106:107], v197 offset:33344
	ds_read_b64_tr_b16 v[108:109], v197 offset:30848
	ds_read_b64_tr_b16 v[110:111], v197 offset:33408
	ds_read_b64_tr_b16 v[112:113], v197 offset:30912
	ds_read_b64_tr_b16 v[114:115], v197 offset:33472
	s_waitcnt lgkmcnt(14)
	v_mfma_f32_32x32x16_bf16 v[68:83], v[10:13], v[226:229], v[68:83]
	s_waitcnt lgkmcnt(12)
	v_mfma_f32_32x32x16_bf16 v[52:67], v[14:17], v[226:229], v[52:67]
	s_waitcnt lgkmcnt(10)
	v_mfma_f32_32x32x16_bf16 v[36:51], v[202:205], v[226:229], v[36:51]
	s_waitcnt lgkmcnt(8)
	v_mfma_f32_32x32x16_bf16 v[20:35], v[206:209], v[226:229], v[20:35]
	ds_read_b64_tr_b16 v[10:11], v197 offset:35840
	ds_read_b64_tr_b16 v[12:13], v197 offset:38400
	ds_read_b64_tr_b16 v[14:15], v197 offset:35904
	ds_read_b64_tr_b16 v[16:17], v197 offset:38464
	ds_read_b64_tr_b16 v[202:203], v197 offset:35968
	ds_read_b64_tr_b16 v[204:205], v197 offset:38528
	ds_read_b64_tr_b16 v[206:207], v197 offset:36032
	ds_read_b64_tr_b16 v[208:209], v197 offset:38592
	v_cvt_pk_bf16_f32 v226, v84, v85
	v_cvt_pk_bf16_f32 v227, v86, v87
	v_cvt_pk_bf16_f32 v228, v88, v89
	v_cvt_pk_bf16_f32 v229, v90, v91
	s_waitcnt lgkmcnt(14)
	v_mfma_f32_32x32x16_bf16 v[68:83], v[100:103], v[230:233], v[68:83]
	s_waitcnt lgkmcnt(12)
	v_mfma_f32_32x32x16_bf16 v[52:67], v[104:107], v[230:233], v[52:67]
	s_waitcnt lgkmcnt(10)
	v_mfma_f32_32x32x16_bf16 v[36:51], v[108:111], v[230:233], v[36:51]
	s_waitcnt lgkmcnt(8)
	v_mfma_f32_32x32x16_bf16 v[20:35], v[112:115], v[230:233], v[20:35]
	ds_read_b64_tr_b16 v[100:101], v197 offset:40960
	ds_read_b64_tr_b16 v[102:103], v197 offset:43520
	ds_read_b64_tr_b16 v[104:105], v197 offset:41024
	ds_read_b64_tr_b16 v[106:107], v197 offset:43584
	ds_read_b64_tr_b16 v[108:109], v197 offset:41088
	ds_read_b64_tr_b16 v[110:111], v197 offset:43648
	ds_read_b64_tr_b16 v[112:113], v197 offset:41152
	ds_read_b64_tr_b16 v[114:115], v197 offset:43712
	v_cvt_pk_bf16_f32 v230, v92, v93
	v_cvt_pk_bf16_f32 v231, v94, v95
	v_cvt_pk_bf16_f32 v232, v96, v97
	v_cvt_pk_bf16_f32 v233, v98, v99
	s_waitcnt lgkmcnt(14)
	v_mfma_f32_32x32x16_bf16 v[68:83], v[10:13], v[226:229], v[68:83]
	s_waitcnt lgkmcnt(12)
	v_mfma_f32_32x32x16_bf16 v[52:67], v[14:17], v[226:229], v[52:67]
	s_waitcnt lgkmcnt(10)
	v_mfma_f32_32x32x16_bf16 v[36:51], v[202:205], v[226:229], v[36:51]
	s_waitcnt lgkmcnt(8)
	v_mfma_f32_32x32x16_bf16 v[20:35], v[206:209], v[226:229], v[20:35]
	s_waitcnt lgkmcnt(6)
	v_mfma_f32_32x32x16_bf16 v[68:83], v[100:103], v[230:233], v[68:83]
	s_waitcnt lgkmcnt(4)
	v_mfma_f32_32x32x16_bf16 v[52:67], v[104:107], v[230:233], v[52:67]
	s_waitcnt lgkmcnt(2)
	v_mfma_f32_32x32x16_bf16 v[36:51], v[108:111], v[230:233], v[36:51]
	s_waitcnt lgkmcnt(0)
	v_mfma_f32_32x32x16_bf16 v[20:35], v[112:115], v[230:233], v[20:35]

.Lm_R:
	s_waitcnt lgkmcnt(0)
	ds_read_b128 v[10:13], v8
	ds_read_b128 v[14:17], v8 offset:32
	ds_read_b128 v[202:205], v8 offset:64
	ds_read_b128 v[206:209], v8 offset:96
	s_waitcnt lgkmcnt(3)
	v_mfma_f32_32x32x16_bf16 v[100:115], v[10:13], v[116:119], v[210:225]
	ds_read_b128 v[10:13], v8 offset:128
	s_waitcnt lgkmcnt(3)
	v_mfma_f32_32x32x16_bf16 v[100:115], v[14:17], v[120:123], v[100:115]
	ds_read_b128 v[14:17], v8 offset:160
	s_waitcnt lgkmcnt(3)
	v_mfma_f32_32x32x16_bf16 v[100:115], v[202:205], v[124:127], v[100:115]
	ds_read_b128 v[202:205], v8 offset:192
	s_waitcnt lgkmcnt(3)
	v_mfma_f32_32x32x16_bf16 v[100:115], v[206:209], v[132:135], v[100:115]
	ds_read_b128 v[206:209], v8 offset:224
	s_waitcnt lgkmcnt(3)
	v_mfma_f32_32x32x16_bf16 v[100:115], v[10:13], v[136:139], v[100:115]
	ds_read_b128 v[10:13], v8 offset:256
	s_waitcnt lgkmcnt(3)
	v_mfma_f32_32x32x16_bf16 v[100:115], v[14:17], v[140:143], v[100:115]
	ds_read_b128 v[14:17], v8 offset:288
	s_waitcnt lgkmcnt(3)
	v_mfma_f32_32x32x16_bf16 v[100:115], v[202:205], v[144:147], v[100:115]
	ds_read_b128 v[202:205], v8 offset:320
	s_waitcnt lgkmcnt(3)
	v_mfma_f32_32x32x16_bf16 v[100:115], v[206:209], v[148:151], v[100:115]
	ds_read_b128 v[206:209], v8 offset:352
	s_waitcnt lgkmcnt(3)
	v_mfma_f32_32x32x16_bf16 v[100:115], v[10:13], v[152:155], v[100:115]
	ds_read_b128 v[10:13], v8 offset:12800
	s_waitcnt lgkmcnt(3)
	v_mfma_f32_32x32x16_bf16 v[100:115], v[14:17], v[156:159], v[100:115]
	ds_read_b128 v[14:17], v8 offset:12832
	s_waitcnt lgkmcnt(3)
	v_mfma_f32_32x32x16_bf16 v[100:115], v[202:205], v[160:163], v[100:115]
	ds_read_b128 v[202:205], v8 offset:12864
	s_waitcnt lgkmcnt(3)
	v_mfma_f32_32x32x16_bf16 v[100:115], v[206:209], v[164:167], v[100:115]
	ds_read_b128 v[206:209], v8 offset:12896
	s_waitcnt lgkmcnt(3)
	v_mfma_f32_32x32x16_bf16 v[84:99], v[10:13], v[116:119], v[210:225]
	ds_read_b128 v[10:13], v8 offset:12928
	s_waitcnt lgkmcnt(3)
	v_mfma_f32_32x32x16_bf16 v[84:99], v[14:17], v[120:123], v[84:99]
	ds_read_b128 v[14:17], v8 offset:12960
	s_waitcnt lgkmcnt(3)
	v_mfma_f32_32x32x16_bf16 v[84:99], v[202:205], v[124:127], v[84:99]
	ds_read_b128 v[202:205], v8 offset:12992
	s_waitcnt lgkmcnt(3)
	v_mfma_f32_32x32x16_bf16 v[84:99], v[206:209], v[132:135], v[84:99]
	ds_read_b128 v[206:209], v8 offset:13024
	s_waitcnt lgkmcnt(3)
	v_mfma_f32_32x32x16_bf16 v[84:99], v[10:13], v[136:139], v[84:99]
	ds_read_b128 v[10:13], v8 offset:13056
	s_waitcnt lgkmcnt(3)
	v_mfma_f32_32x32x16_bf16 v[84:99], v[14:17], v[140:143], v[84:99]
	ds_read_b128 v[14:17], v8 offset:13088
	s_waitcnt lgkmcnt(3)
	v_mfma_f32_32x32x16_bf16 v[84:99], v[202:205], v[144:147], v[84:99]
	ds_read_b128 v[202:205], v8 offset:13120
	s_waitcnt lgkmcnt(3)
	v_mfma_f32_32x32x16_bf16 v[84:99], v[206:209], v[148:151], v[84:99]
	ds_read_b128 v[206:209], v8 offset:13152
	s_waitcnt lgkmcnt(3)
	v_mfma_f32_32x32x16_bf16 v[84:99], v[10:13], v[152:155], v[84:99]
	s_waitcnt lgkmcnt(2)
	v_mfma_f32_32x32x16_bf16 v[84:99], v[14:17], v[156:159], v[84:99]
	s_waitcnt lgkmcnt(1)
	v_mfma_f32_32x32x16_bf16 v[84:99], v[202:205], v[160:163], v[84:99]
	s_waitcnt lgkmcnt(0)
	v_mfma_f32_32x32x16_bf16 v[84:99], v[206:209], v[164:167], v[84:99]
	v_max3_f32 v235, v100, v101, v102
	v_max3_f32 v235, v235, v103, v104
	v_max3_f32 v235, v235, v105, v106
	v_max3_f32 v235, v235, v107, v108
	v_max3_f32 v235, v235, v109, v110
	v_max3_f32 v235, v235, v111, v112
	v_max3_f32 v235, v235, v113, v114
	s_nop 4
	v_max3_f32 v235, v235, v115, v84
	v_max3_f32 v235, v235, v85, v86
	v_max3_f32 v235, v235, v87, v88
	v_max3_f32 v235, v235, v89, v90
	v_max3_f32 v235, v235, v91, v92
	v_max3_f32 v235, v235, v93, v94
	v_max3_f32 v235, v235, v95, v96
	v_max3_f32 v235, v235, v97, v98
	v_max3_f32 v235, v235, v99, v99
	v_mov_b32_e32 v237, v235
	v_mov_b32_e32 v239, v235
	s_nop 1
	v_permlane32_swap_b32_e32 v237, v239
	v_cndmask_b32_e64 v237, v237, v239, s[4:5]
	v_max_f32_e32 v237, v237, v237
	v_max_f32_e32 v236, v235, v237
	v_max_f32_e32 v236, 0, v236
	v_exp_f32_e64 v238, -v236
	v_pk_add_f32 v[100:101], v[100:101], v[236:237] op_sel_hi:[1,0] neg_lo:[0,1] neg_hi:[0,1]
	v_pk_add_f32 v[102:103], v[102:103], v[236:237] op_sel_hi:[1,0] neg_lo:[0,1] neg_hi:[0,1]
	v_pk_add_f32 v[104:105], v[104:105], v[236:237] op_sel_hi:[1,0] neg_lo:[0,1] neg_hi:[0,1]
	v_pk_add_f32 v[106:107], v[106:107], v[236:237] op_sel_hi:[1,0] neg_lo:[0,1] neg_hi:[0,1]
	v_pk_add_f32 v[108:109], v[108:109], v[236:237] op_sel_hi:[1,0] neg_lo:[0,1] neg_hi:[0,1]
	v_pk_add_f32 v[110:111], v[110:111], v[236:237] op_sel_hi:[1,0] neg_lo:[0,1] neg_hi:[0,1]
	v_pk_add_f32 v[112:113], v[112:113], v[236:237] op_sel_hi:[1,0] neg_lo:[0,1] neg_hi:[0,1]
	v_pk_add_f32 v[114:115], v[114:115], v[236:237] op_sel_hi:[1,0] neg_lo:[0,1] neg_hi:[0,1]
	v_pk_add_f32 v[84:85], v[84:85], v[236:237] op_sel_hi:[1,0] neg_lo:[0,1] neg_hi:[0,1]
	v_pk_add_f32 v[86:87], v[86:87], v[236:237] op_sel_hi:[1,0] neg_lo:[0,1] neg_hi:[0,1]
	v_pk_add_f32 v[88:89], v[88:89], v[236:237] op_sel_hi:[1,0] neg_lo:[0,1] neg_hi:[0,1]
	v_pk_add_f32 v[90:91], v[90:91], v[236:237] op_sel_hi:[1,0] neg_lo:[0,1] neg_hi:[0,1]
	v_pk_add_f32 v[92:93], v[92:93], v[236:237] op_sel_hi:[1,0] neg_lo:[0,1] neg_hi:[0,1]
	v_pk_add_f32 v[94:95], v[94:95], v[236:237] op_sel_hi:[1,0] neg_lo:[0,1] neg_hi:[0,1]
	v_pk_add_f32 v[96:97], v[96:97], v[236:237] op_sel_hi:[1,0] neg_lo:[0,1] neg_hi:[0,1]
	v_pk_add_f32 v[98:99], v[98:99], v[236:237] op_sel_hi:[1,0] neg_lo:[0,1] neg_hi:[0,1]
	v_pk_add_f32 v[210:211], v[210:211], v[236:237] op_sel_hi:[1,0] neg_lo:[0,1] neg_hi:[0,1]
	v_pk_add_f32 v[212:213], v[212:213], v[236:237] op_sel_hi:[1,0] neg_lo:[0,1] neg_hi:[0,1]
	v_pk_add_f32 v[214:215], v[214:215], v[236:237] op_sel_hi:[1,0] neg_lo:[0,1] neg_hi:[0,1]
	v_pk_add_f32 v[216:217], v[216:217], v[236:237] op_sel_hi:[1,0] neg_lo:[0,1] neg_hi:[0,1]
	v_pk_add_f32 v[218:219], v[218:219], v[236:237] op_sel_hi:[1,0] neg_lo:[0,1] neg_hi:[0,1]
	v_pk_add_f32 v[220:221], v[220:221], v[236:237] op_sel_hi:[1,0] neg_lo:[0,1] neg_hi:[0,1]
	v_pk_add_f32 v[222:223], v[222:223], v[236:237] op_sel_hi:[1,0] neg_lo:[0,1] neg_hi:[0,1]
	v_pk_add_f32 v[224:225], v[224:225], v[236:237] op_sel_hi:[1,0] neg_lo:[0,1] neg_hi:[0,1]
	v_mul_f32_e32 v193, v193, v238
	v_pk_mul_f32 v[68:69], v[68:69], v[238:239] op_sel_hi:[1,0]
	v_pk_mul_f32 v[70:71], v[70:71], v[238:239] op_sel_hi:[1,0]
	v_pk_mul_f32 v[72:73], v[72:73], v[238:239] op_sel_hi:[1,0]
	v_pk_mul_f32 v[74:75], v[74:75], v[238:239] op_sel_hi:[1,0]
	v_pk_mul_f32 v[76:77], v[76:77], v[238:239] op_sel_hi:[1,0]
	v_pk_mul_f32 v[78:79], v[78:79], v[238:239] op_sel_hi:[1,0]
	v_pk_mul_f32 v[80:81], v[80:81], v[238:239] op_sel_hi:[1,0]
	v_pk_mul_f32 v[82:83], v[82:83], v[238:239] op_sel_hi:[1,0]
	v_pk_mul_f32 v[52:53], v[52:53], v[238:239] op_sel_hi:[1,0]
	v_pk_mul_f32 v[54:55], v[54:55], v[238:239] op_sel_hi:[1,0]
	v_pk_mul_f32 v[56:57], v[56:57], v[238:239] op_sel_hi:[1,0]
	v_pk_mul_f32 v[58:59], v[58:59], v[238:239] op_sel_hi:[1,0]
	v_pk_mul_f32 v[60:61], v[60:61], v[238:239] op_sel_hi:[1,0]
	v_pk_mul_f32 v[62:63], v[62:63], v[238:239] op_sel_hi:[1,0]
	v_pk_mul_f32 v[64:65], v[64:65], v[238:239] op_sel_hi:[1,0]
	v_pk_mul_f32 v[66:67], v[66:67], v[238:239] op_sel_hi:[1,0]
	v_pk_mul_f32 v[36:37], v[36:37], v[238:239] op_sel_hi:[1,0]
	v_pk_mul_f32 v[38:39], v[38:39], v[238:239] op_sel_hi:[1,0]
	v_pk_mul_f32 v[40:41], v[40:41], v[238:239] op_sel_hi:[1,0]
	v_pk_mul_f32 v[42:43], v[42:43], v[238:239] op_sel_hi:[1,0]
	v_pk_mul_f32 v[44:45], v[44:45], v[238:239] op_sel_hi:[1,0]
	v_pk_mul_f32 v[46:47], v[46:47], v[238:239] op_sel_hi:[1,0]
	v_pk_mul_f32 v[48:49], v[48:49], v[238:239] op_sel_hi:[1,0]
	v_pk_mul_f32 v[50:51], v[50:51], v[238:239] op_sel_hi:[1,0]
	v_pk_mul_f32 v[20:21], v[20:21], v[238:239] op_sel_hi:[1,0]
	v_pk_mul_f32 v[22:23], v[22:23], v[238:239] op_sel_hi:[1,0]
	v_pk_mul_f32 v[24:25], v[24:25], v[238:239] op_sel_hi:[1,0]
	v_pk_mul_f32 v[26:27], v[26:27], v[238:239] op_sel_hi:[1,0]
	v_pk_mul_f32 v[28:29], v[28:29], v[238:239] op_sel_hi:[1,0]
	v_pk_mul_f32 v[30:31], v[30:31], v[238:239] op_sel_hi:[1,0]
	v_pk_mul_f32 v[32:33], v[32:33], v[238:239] op_sel_hi:[1,0]
	v_pk_mul_f32 v[34:35], v[34:35], v[238:239] op_sel_hi:[1,0]
	v_add_f32_e32 v192, v192, v236
	ds_read_b64_tr_b16 v[10:11], v197 offset:25600
	ds_read_b64_tr_b16 v[12:13], v197 offset:28160
	ds_read_b64_tr_b16 v[14:15], v197 offset:25664
	ds_read_b64_tr_b16 v[16:17], v197 offset:28224
	ds_read_b64_tr_b16 v[202:203], v197 offset:25728
	ds_read_b64_tr_b16 v[204:205], v197 offset:28288
	ds_read_b64_tr_b16 v[206:207], v197 offset:25792
	ds_read_b64_tr_b16 v[208:209], v197 offset:28352
	s_branch .Lm_exp
